# P10 tile epilogue: LayerNorm-fold column vectors prefetched at tile start into spare VGPRs instead of loaded and waited at epilogue start
# baseline (speedup 1.0000x reference)
;     __device__ __forceinline__ void operator()(const f32x4 (&acc)[2][2][4][2], const Unit& u, int wr, int wc, int fr_, int fq_, LAS unsigned char* ldsx) const {
;     ...
;         f32x4 av[2][2], bv[2][2], cv[2][2];
; #pragma unroll
;         for (int bj = 0; bj < 2; ++bj)
; #pragma unroll
;             for (int n = 0; n < 2; ++n) { av[bj][n] = CONS ? *(const f32x4*)(va + colb + bj * HALF + 4 * n) : z; bv[bj][n] = CONS ? *(const f32x4*)(vb + colb + bj * HALF + 4 * n) : z;
;                                           cv[bj][n] = (MODE == 5) ? *(const f32x4*)(bias + colb + bj * HALF + 4 * n) : z; }
.LBB0_1370:
	s_add_i32 s98, s36, s60
	v_lshl_add_u32 v248, v179, 3, s98
	v_ashrrev_i32_e32 v249, 31, v248
	v_lshlrev_b64 v[250:251], 2, v[248:249]
	v_lshl_add_u64 v[248:249], s[0:1], 0, v[250:251]
	global_load_dwordx4 v[216:219], v[248:249], off
	global_load_dwordx4 v[220:223], v[248:249], off offset:16
	global_load_dwordx4 v[224:227], v[248:249], off offset:512
	global_load_dwordx4 v[228:231], v[248:249], off offset:528
	v_lshl_add_u64 v[250:251], s[8:9], 0, v[250:251]
	global_load_dwordx4 v[232:235], v[250:251], off
	global_load_dwordx4 v[236:239], v[250:251], off offset:16
	global_load_dwordx4 v[240:243], v[250:251], off offset:512
	global_load_dwordx4 v[244:247], v[250:251], off offset:528
	s_add_i32 s66, s21, 1
	s_cmp_ge_i32 s66, s3
	s_mov_b64 s[28:29], 0
	s_cbranch_scc1 .LBB0_1377
	s_sub_i32 s21, s63, s21
	s_mul_hi_i32 s25, s21, s96
	s_mul_i32 s21, s21, s96
	s_add_u32 s30, s21, s2
	s_addc_u32 s31, s25, s85
	v_cmp_gt_i64_e32 vcc, s[30:31], v[172:173]
	s_cbranch_vccnz .LBB0_1377
	s_ashr_i32 s21, s30, 31
	s_lshr_b32 s21, s21, 29
	s_add_i32 s21, s30, s21
	s_and_b32 s24, s21, -8
	s_sub_i32 s26, s30, s24
	s_cmp_gt_i32 s26, -1
	s_mov_b64 s[24:25], -1
	s_cbranch_scc0 .LBB0_1374
	s_lshl_b32 s27, s26, 8
	s_mov_b64 s[24:25], 0

; #define EPI_FOR_ROWS for (int ai = 0; ai < 2; ++ai) _Pragma("unroll") for (int m = 0; m < 4; ++m)
;     __device__ __forceinline__ void piece(size_t row, int col, f32x4 v0, f32x4 v1, const f32x4 a0, const f32x4 a1, const f32x4 b0, const f32x4 b1, const f32x4 c0, const f32x4 c1,
;                                           float mean, float rstd, float& s, float& ss) const {
;     ...
;         if constexpr (MODE == 4) { v0 = (v0 - a0 * mean) * rstd + b0; v1 = (v1 - a1 * mean) * rstd + b1;
; #pragma unroll
;             for (int e = 0; e < 4; ++e) { const float x = fmaxf(v0[e], 0.f), y = fmaxf(v1[e], 0.f); v0[e] = x * x; v1[e] = y * y; } }
;     __device__ __forceinline__ void operator()(const f32x4 (&acc)[2][2][4][2], const Unit& u, int wr, int wc, int fr_, int fq_, LAS unsigned char* ldsx) const {
;     ...
;         EPI_FOR_ROWS {
;             const int rl = ai * HALF + wr * 64 + m * 16 + fr; const size_t row = (size_t)u.row0 + rl;
;             float mean = 0.f, rstd = 0.f; if constexpr (CONS) { const f32x2 st = X[rl]; mean = st.x; rstd = st.y; }
;             float s = 0.f, ss = 0.f;
; #pragma unroll
;             for (int bj = 0; bj < 2; ++bj) piece(row, colb + bj * HALF, acc[ai][bj][m][0], acc[ai][bj][m][1], av[bj][0], av[bj][1], bv[bj][0], bv[bj][1], cv[bj][0], cv[bj][1], mean, rstd, s, ss);
.LBB0_1381:
	s_cmp_eq_u32 s20, s10
	v_mov_b32_e32 v174, v178
	v_mov_b32_e32 v128, v179
	s_cselect_b32 s25, 0, 0x800
	s_add_i32 s21, s36, s60
	s_add_i32 s25, s25, 0
	v_lshl_add_u32 v176, v128, 3, s21
	v_ashrrev_i32_e32 v177, 31, v176
	v_lshlrev_b64 v[132:133], 2, v[176:177]
	v_lshl_add_u64 v[128:129], s[0:1], 0, v[132:133]
	v_mov_b64_e32 v[148:149], v[216:217]
	v_mov_b64_e32 v[150:151], v[218:219]
	v_mov_b64_e32 v[144:145], v[220:221]
	v_mov_b64_e32 v[146:147], v[222:223]
	v_mov_b64_e32 v[136:137], v[224:225]
	v_mov_b64_e32 v[138:139], v[226:227]
	s_nop 0
	v_mov_b64_e32 v[128:129], v[228:229]
	v_mov_b64_e32 v[130:131], v[230:231]
	v_lshl_add_u64 v[132:133], s[8:9], 0, v[132:133]
	v_mov_b64_e32 v[156:157], v[232:233]
	v_mov_b64_e32 v[158:159], v[234:235]
	v_mov_b64_e32 v[152:153], v[236:237]
	v_mov_b64_e32 v[154:155], v[238:239]
	v_mov_b64_e32 v[140:141], v[240:241]
	v_mov_b64_e32 v[142:143], v[242:243]
	s_nop 0
	v_mov_b64_e32 v[132:133], v[244:245]
	v_mov_b64_e32 v[134:135], v[246:247]
	v_add_u32_e32 v174, s43, v174
	s_ashr_i32 s21, s20, 31
	v_lshl_add_u32 v184, v174, 3, s25
	v_ashrrev_i32_e32 v175, 31, v174
	v_lshl_add_u64 v[188:189], v[174:175], 0, s[20:21]
	v_add_u32_e32 v175, 0x20000, v184
	ds_read2_b64 v[184:187], v175 offset1:16
	v_lshlrev_b64 v[188:189], 13, v[188:189]
	v_lshlrev_b64 v[176:177], 1, v[176:177]
	v_lshl_add_u64 v[188:189], s[44:45], 0, v[188:189]
	v_lshl_add_u64 v[192:193], v[188:189], 0, v[176:177]
	s_andn2_b64 vcc, exec, s[28:29]
	s_waitcnt vmcnt(0)
	v_xor_b32_e32 v151, 0x80000000, v151
	v_xor_b32_e32 v150, 0x80000000, v150
	s_waitcnt lgkmcnt(0)
	v_pk_fma_f32 v[188:189], v[148:149], v[184:185], v[124:125] op_sel_hi:[1,0,1] neg_lo:[1,0,0] neg_hi:[1,0,0]
	v_xor_b32_e32 v125, 0x80000000, v147
	v_xor_b32_e32 v124, 0x80000000, v146
	v_pk_fma_f32 v[146:147], v[144:145], v[184:185], v[120:121] op_sel_hi:[1,0,1] neg_lo:[1,0,0] neg_hi:[1,0,0]
	v_xor_b32_e32 v121, 0x80000000, v139
	v_xor_b32_e32 v120, 0x80000000, v138
	v_pk_fma_f32 v[138:139], v[136:137], v[184:185], v[116:117] op_sel_hi:[1,0,1] neg_lo:[1,0,0] neg_hi:[1,0,0]
	v_xor_b32_e32 v117, 0x80000000, v131
	v_xor_b32_e32 v116, 0x80000000, v130
	v_pk_fma_f32 v[112:113], v[128:129], v[184:185], v[112:113] op_sel_hi:[1,0,1] neg_lo:[1,0,0] neg_hi:[1,0,0]
	v_pk_fma_f32 v[126:127], v[150:151], v[184:185], v[126:127] op_sel_hi:[1,0,1]
	v_pk_fma_f32 v[130:131], v[184:185], v[188:189], v[156:157] op_sel:[1,0,0]
	v_pk_fma_f32 v[122:123], v[124:125], v[184:185], v[122:123] op_sel_hi:[1,0,1]
	v_pk_fma_f32 v[118:119], v[120:121], v[184:185], v[118:119] op_sel_hi:[1,0,1]
	v_pk_fma_f32 v[114:115], v[116:117], v[184:185], v[114:115] op_sel_hi:[1,0,1]
	v_pk_fma_f32 v[112:113], v[184:185], v[112:113], v[132:133] op_sel:[1,0,0]
	v_pk_fma_f32 v[146:147], v[184:185], v[146:147], v[152:153] op_sel:[1,0,0]
	v_pk_fma_f32 v[126:127], v[184:185], v[126:127], v[158:159] op_sel:[1,0,0]
	v_pk_fma_f32 v[122:123], v[184:185], v[122:123], v[154:155] op_sel:[1,0,0]
	v_max_f32_e32 v130, 0, v130
	v_max_f32_e32 v131, 0, v131
	v_pk_fma_f32 v[118:119], v[184:185], v[118:119], v[142:143] op_sel:[1,0,0]
	v_pk_fma_f32 v[114:115], v[184:185], v[114:115], v[134:135] op_sel:[1,0,0]
	v_max_f32_e32 v112, 0, v112
	v_max_f32_e32 v113, 0, v113
	v_pk_fma_f32 v[106:107], v[124:125], v[186:187], v[106:107] op_sel_hi:[1,0,1]
	v_pk_fma_f32 v[104:105], v[144:145], v[186:187], v[104:105] op_sel_hi:[1,0,1] neg_lo:[1,0,0] neg_hi:[1,0,0]
	v_pk_fma_f32 v[138:139], v[184:185], v[138:139], v[140:141] op_sel:[1,0,0]
	v_max_f32_e32 v146, 0, v146
	v_max_f32_e32 v147, 0, v147
	v_mul_f32_e32 v130, v130, v130
	v_mul_f32_e32 v131, v131, v131
	v_max_f32_e32 v126, 0, v126
	v_max_f32_e32 v122, 0, v122
	v_max_f32_e32 v127, 0, v127
	v_max_f32_e32 v123, 0, v123
	v_mul_f32_e32 v184, v112, v112
	v_mul_f32_e32 v185, v113, v113
	v_max_f32_e32 v113, 0, v118
	v_max_f32_e32 v115, 0, v115
	v_cvt_pk_bf16_f32 v112, v130, v131
	v_pk_fma_f32 v[110:111], v[150:151], v[186:187], v[110:111] op_sel_hi:[1,0,1]
	v_pk_fma_f32 v[108:109], v[148:149], v[186:187], v[108:109] op_sel_hi:[1,0,1] neg_lo:[1,0,0] neg_hi:[1,0,0]
	v_pk_fma_f32 v[106:107], v[186:187], v[106:107], v[154:155] op_sel:[1,0,0]
	v_pk_fma_f32 v[104:105], v[186:187], v[104:105], v[152:153] op_sel:[1,0,0]
	v_mul_f32_e32 v146, v146, v146
	v_mul_f32_e32 v147, v147, v147
	v_max_f32_e32 v118, 0, v114
	v_mul_f32_e32 v126, v126, v126
	v_mul_f32_e32 v122, v122, v122
	v_mul_f32_e32 v127, v127, v127
	v_mul_f32_e32 v123, v123, v123
	v_cvt_pk_bf16_f32 v114, v146, v147
	v_mul_f32_e32 v130, v113, v113
	v_mul_f32_e32 v131, v115, v115
	v_cvt_pk_bf16_f32 v113, v126, v127
	v_cvt_pk_bf16_f32 v115, v122, v123
	global_store_dwordx4 v[192:193], v[112:115], off
	v_pk_fma_f32 v[110:111], v[186:187], v[110:111], v[158:159] op_sel:[1,0,0]
	v_pk_fma_f32 v[108:109], v[186:187], v[108:109], v[156:157] op_sel:[1,0,0]
	v_add_u32_e32 v112, 16, v174
	v_max_f32_e32 v104, 0, v104
	v_max_f32_e32 v105, 0, v105
	v_max_f32_e32 v106, 0, v106
	v_ashrrev_i32_e32 v113, 31, v112
	v_max_f32_e32 v108, 0, v108
	v_mul_f32_e32 v114, v104, v104
	v_max_f32_e32 v104, 0, v109
	v_mul_f32_e32 v109, v105, v105
	v_max_f32_e32 v105, 0, v110
	v_mul_f32_e32 v110, v106, v106
	v_max_f32_e32 v106, 0, v111
	v_lshl_add_u64 v[112:113], v[112:113], 0, s[20:21]
	v_mul_f32_e32 v108, v108, v108
	v_mul_f32_e32 v104, v104, v104
	v_mul_f32_e32 v105, v105, v105
	v_mul_f32_e32 v106, v106, v106
	v_cvt_pk_bf16_f32 v104, v108, v104
	v_cvt_pk_bf16_f32 v105, v105, v106
	v_cvt_pk_bf16_f32 v106, v114, v109
	v_lshlrev_b64 v[108:109], 13, v[112:113]
	v_pk_fma_f32 v[98:99], v[116:117], v[186:187], v[98:99] op_sel_hi:[1,0,1]
	v_pk_fma_f32 v[96:97], v[128:129], v[186:187], v[96:97] op_sel_hi:[1,0,1] neg_lo:[1,0,0] neg_hi:[1,0,0]
; #define EPI_FOR_ROWS for (int ai = 0; ai < 2; ++ai) _Pragma("unroll") for (int m = 0; m < 4; ++m)
;     __device__ __forceinline__ void piece(size_t row, int col, f32x4 v0, f32x4 v1, const f32x4 a0, const f32x4 a1, const f32x4 b0, const f32x4 b1, const f32x4 c0, const f32x4 c1,
;                                           float mean, float rstd, float& s, float& ss) const {
;     ...
;         if constexpr (MODE == 4) { v0 = (v0 - a0 * mean) * rstd + b0; v1 = (v1 - a1 * mean) * rstd + b1;
; #pragma unroll
;             for (int e = 0; e < 4; ++e) { const float x = fmaxf(v0[e], 0.f), y = fmaxf(v1[e], 0.f); v0[e] = x * x; v1[e] = y * y; } }
;     __device__ __forceinline__ void operator()(const f32x4 (&acc)[2][2][4][2], const Unit& u, int wr, int wc, int fr_, int fq_, LAS unsigned char* ldsx) const {
;     ...
;         EPI_FOR_ROWS {
;             const int rl = ai * HALF + wr * 64 + m * 16 + fr; const size_t row = (size_t)u.row0 + rl;
;             float mean = 0.f, rstd = 0.f; if constexpr (CONS) { const f32x2 st = X[rl]; mean = st.x; rstd = st.y; }
;             float s = 0.f, ss = 0.f;
; #pragma unroll
;             for (int bj = 0; bj < 2; ++bj) piece(row, colb + bj * HALF, acc[ai][bj][m][0], acc[ai][bj][m][1], av[bj][0], av[bj][1], bv[bj][0], bv[bj][1], cv[bj][0], cv[bj][1], mean, rstd, s, ss);
	v_max_f32_e32 v107, 0, v107
	v_lshl_add_u64 v[108:109], s[44:45], 0, v[108:109]
	v_pk_fma_f32 v[102:103], v[120:121], v[186:187], v[102:103] op_sel_hi:[1,0,1]
	v_pk_fma_f32 v[100:101], v[136:137], v[186:187], v[100:101] op_sel_hi:[1,0,1] neg_lo:[1,0,0] neg_hi:[1,0,0]
	v_pk_fma_f32 v[98:99], v[186:187], v[98:99], v[134:135] op_sel:[1,0,0]
	v_pk_fma_f32 v[96:97], v[186:187], v[96:97], v[132:133] op_sel:[1,0,0]
	v_mul_f32_e32 v107, v107, v107
	v_lshl_add_u64 v[108:109], v[108:109], 0, v[176:177]
	v_pk_fma_f32 v[102:103], v[186:187], v[102:103], v[142:143] op_sel:[1,0,0]
	v_pk_fma_f32 v[100:101], v[186:187], v[100:101], v[140:141] op_sel:[1,0,0]
	v_max_f32_e32 v96, 0, v96
	v_max_f32_e32 v97, 0, v97
	v_max_f32_e32 v98, 0, v98
	v_cvt_pk_bf16_f32 v107, v110, v107
	global_store_dwordx4 v[108:109], v[104:107], off
	v_max_f32_e32 v100, 0, v100
	v_max_f32_e32 v99, 0, v99
	v_mul_f32_e32 v104, v96, v96
	v_max_f32_e32 v96, 0, v101
	v_mul_f32_e32 v101, v97, v97
	v_max_f32_e32 v97, 0, v102
	v_mul_f32_e32 v102, v98, v98
	v_max_f32_e32 v98, 0, v103
	v_mul_f32_e32 v100, v100, v100
	v_mul_f32_e32 v96, v96, v96
	v_mul_f32_e32 v97, v97, v97
	v_mul_f32_e32 v98, v98, v98
	v_mul_f32_e32 v99, v99, v99
	v_cvt_pk_bf16_f32 v96, v100, v96
	v_cvt_pk_bf16_f32 v97, v97, v98
	v_cvt_pk_bf16_f32 v98, v104, v101
	v_cvt_pk_bf16_f32 v99, v102, v99
	ds_read2_b64 v[100:103], v175 offset0:32 offset1:48
	global_store_dwordx4 v[108:109], v[96:99], off offset:256
	v_max_f32_e32 v138, 0, v138
	v_max_f32_e32 v139, 0, v139
	v_add_u32_e32 v96, 32, v174
	s_waitcnt lgkmcnt(0)
	v_pk_fma_f32 v[90:91], v[124:125], v[100:101], v[90:91] op_sel_hi:[1,0,1]
	v_pk_fma_f32 v[88:89], v[144:145], v[100:101], v[88:89] op_sel_hi:[1,0,1] neg_lo:[1,0,0] neg_hi:[1,0,0]
	v_pk_fma_f32 v[94:95], v[150:151], v[100:101], v[94:95] op_sel_hi:[1,0,1]
	v_pk_fma_f32 v[92:93], v[148:149], v[100:101], v[92:93] op_sel_hi:[1,0,1] neg_lo:[1,0,0] neg_hi:[1,0,0]
	v_pk_fma_f32 v[90:91], v[100:101], v[90:91], v[154:155] op_sel:[1,0,0]
	v_pk_fma_f32 v[88:89], v[100:101], v[88:89], v[152:153] op_sel:[1,0,0]
	v_pk_fma_f32 v[94:95], v[100:101], v[94:95], v[158:159] op_sel:[1,0,0]
	v_pk_fma_f32 v[92:93], v[100:101], v[92:93], v[156:157] op_sel:[1,0,0]
	v_max_f32_e32 v88, 0, v88
	v_max_f32_e32 v89, 0, v89
	v_max_f32_e32 v90, 0, v90
	v_ashrrev_i32_e32 v97, 31, v96
	v_max_f32_e32 v92, 0, v92
	v_mul_f32_e32 v98, v88, v88
	v_max_f32_e32 v88, 0, v93
	v_mul_f32_e32 v93, v89, v89
	v_max_f32_e32 v89, 0, v94
	v_mul_f32_e32 v94, v90, v90
	v_max_f32_e32 v90, 0, v95
	v_lshl_add_u64 v[96:97], v[96:97], 0, s[20:21]
	v_mul_f32_e32 v92, v92, v92
	v_mul_f32_e32 v88, v88, v88
	v_mul_f32_e32 v89, v89, v89
	v_mul_f32_e32 v90, v90, v90
	v_cvt_pk_bf16_f32 v88, v92, v88
	v_cvt_pk_bf16_f32 v89, v89, v90
	v_cvt_pk_bf16_f32 v90, v98, v93
	v_lshlrev_b64 v[92:93], 13, v[96:97]
	v_pk_fma_f32 v[80:81], v[128:129], v[100:101], v[80:81] op_sel_hi:[1,0,1] neg_lo:[1,0,0] neg_hi:[1,0,0]
	v_max_f32_e32 v91, 0, v91
	v_lshl_add_u64 v[92:93], s[44:45], 0, v[92:93]
	v_pk_fma_f32 v[84:85], v[136:137], v[100:101], v[84:85] op_sel_hi:[1,0,1] neg_lo:[1,0,0] neg_hi:[1,0,0]
	v_pk_fma_f32 v[82:83], v[116:117], v[100:101], v[82:83] op_sel_hi:[1,0,1]
	v_pk_fma_f32 v[80:81], v[100:101], v[80:81], v[132:133] op_sel:[1,0,0]
	v_mul_f32_e32 v91, v91, v91
	v_lshl_add_u64 v[92:93], v[92:93], 0, v[176:177]
	v_pk_fma_f32 v[86:87], v[120:121], v[100:101], v[86:87] op_sel_hi:[1,0,1]
	v_pk_fma_f32 v[84:85], v[100:101], v[84:85], v[140:141] op_sel:[1,0,0]
	v_pk_fma_f32 v[82:83], v[100:101], v[82:83], v[134:135] op_sel:[1,0,0]
	v_max_f32_e32 v80, 0, v80
	v_cvt_pk_bf16_f32 v91, v94, v91
	global_store_dwordx4 v[92:93], v[88:91], off
	v_pk_fma_f32 v[86:87], v[100:101], v[86:87], v[142:143] op_sel:[1,0,0]
	v_max_f32_e32 v81, 0, v81
	v_mul_f32_e32 v88, v80, v80
	v_max_f32_e32 v80, 0, v85
	v_max_f32_e32 v82, 0, v82
	v_max_f32_e32 v84, 0, v84
	v_mul_f32_e32 v80, v80, v80
	v_mul_f32_e32 v85, v81, v81
	v_max_f32_e32 v81, 0, v86
	v_mul_f32_e32 v86, v82, v82
	v_max_f32_e32 v82, 0, v87
	v_max_f32_e32 v83, 0, v83
	v_pk_fma_f32 v[74:75], v[124:125], v[102:103], v[74:75] op_sel_hi:[1,0,1]
	v_pk_fma_f32 v[72:73], v[144:145], v[102:103], v[72:73] op_sel_hi:[1,0,1] neg_lo:[1,0,0] neg_hi:[1,0,0]
	v_mul_f32_e32 v84, v84, v84
	v_mul_f32_e32 v81, v81, v81
	v_mul_f32_e32 v82, v82, v82
	v_mul_f32_e32 v83, v83, v83
	v_cvt_pk_bf16_f32 v80, v84, v80
	v_pk_fma_f32 v[78:79], v[150:151], v[102:103], v[78:79] op_sel_hi:[1,0,1]
	v_pk_fma_f32 v[76:77], v[148:149], v[102:103], v[76:77] op_sel_hi:[1,0,1] neg_lo:[1,0,0] neg_hi:[1,0,0]
	v_pk_fma_f32 v[74:75], v[102:103], v[74:75], v[154:155] op_sel:[1,0,0]
	v_pk_fma_f32 v[72:73], v[102:103], v[72:73], v[152:153] op_sel:[1,0,0]
	v_cvt_pk_bf16_f32 v81, v81, v82
	v_cvt_pk_bf16_f32 v82, v88, v85
	v_cvt_pk_bf16_f32 v83, v86, v83
	global_store_dwordx4 v[92:93], v[80:83], off offset:256
	v_pk_fma_f32 v[78:79], v[102:103], v[78:79], v[158:159] op_sel:[1,0,0]
	v_pk_fma_f32 v[76:77], v[102:103], v[76:77], v[156:157] op_sel:[1,0,0]
	v_add_u32_e32 v80, 48, v174
	v_max_f32_e32 v72, 0, v72
	v_max_f32_e32 v73, 0, v73
	v_max_f32_e32 v74, 0, v74
	v_ashrrev_i32_e32 v81, 31, v80
	v_max_f32_e32 v76, 0, v76
	v_mul_f32_e32 v82, v72, v72
	v_max_f32_e32 v72, 0, v77
	v_mul_f32_e32 v77, v73, v73
	v_max_f32_e32 v73, 0, v78
	v_mul_f32_e32 v78, v74, v74
	v_max_f32_e32 v74, 0, v79
	v_lshl_add_u64 v[80:81], v[80:81], 0, s[20:21]
	v_mul_f32_e32 v76, v76, v76
	v_mul_f32_e32 v72, v72, v72
	v_mul_f32_e32 v73, v73, v73
	v_mul_f32_e32 v74, v74, v74
	v_cvt_pk_bf16_f32 v72, v76, v72
	v_cvt_pk_bf16_f32 v73, v73, v74
	v_cvt_pk_bf16_f32 v74, v82, v77
	v_lshlrev_b64 v[76:77], 13, v[80:81]
; #define EPI_FOR_ROWS for (int ai = 0; ai < 2; ++ai) _Pragma("unroll") for (int m = 0; m < 4; ++m)
;     __device__ __forceinline__ void piece(size_t row, int col, f32x4 v0, f32x4 v1, const f32x4 a0, const f32x4 a1, const f32x4 b0, const f32x4 b1, const f32x4 c0, const f32x4 c1,
;                                           float mean, float rstd, float& s, float& ss) const {
;     ...
;         if constexpr (MODE == 4) { v0 = (v0 - a0 * mean) * rstd + b0; v1 = (v1 - a1 * mean) * rstd + b1;
; #pragma unroll
;             for (int e = 0; e < 4; ++e) { const float x = fmaxf(v0[e], 0.f), y = fmaxf(v1[e], 0.f); v0[e] = x * x; v1[e] = y * y; } }
;     __device__ __forceinline__ void operator()(const f32x4 (&acc)[2][2][4][2], const Unit& u, int wr, int wc, int fr_, int fq_, LAS unsigned char* ldsx) const {
;     ...
;         EPI_FOR_ROWS {
;             const int rl = ai * HALF + wr * 64 + m * 16 + fr; const size_t row = (size_t)u.row0 + rl;
;             float mean = 0.f, rstd = 0.f; if constexpr (CONS) { const f32x2 st = X[rl]; mean = st.x; rstd = st.y; }
;             float s = 0.f, ss = 0.f;
; #pragma unroll
;             for (int bj = 0; bj < 2; ++bj) piece(row, colb + bj * HALF, acc[ai][bj][m][0], acc[ai][bj][m][1], av[bj][0], av[bj][1], bv[bj][0], bv[bj][1], cv[bj][0], cv[bj][1], mean, rstd, s, ss);
	v_pk_fma_f32 v[66:67], v[116:117], v[102:103], v[66:67] op_sel_hi:[1,0,1]
	v_pk_fma_f32 v[64:65], v[128:129], v[102:103], v[64:65] op_sel_hi:[1,0,1] neg_lo:[1,0,0] neg_hi:[1,0,0]
	v_max_f32_e32 v75, 0, v75
	v_lshl_add_u64 v[76:77], s[44:45], 0, v[76:77]
	v_pk_fma_f32 v[70:71], v[120:121], v[102:103], v[70:71] op_sel_hi:[1,0,1]
	v_pk_fma_f32 v[68:69], v[136:137], v[102:103], v[68:69] op_sel_hi:[1,0,1] neg_lo:[1,0,0] neg_hi:[1,0,0]
	v_pk_fma_f32 v[66:67], v[102:103], v[66:67], v[134:135] op_sel:[1,0,0]
	v_pk_fma_f32 v[64:65], v[102:103], v[64:65], v[132:133] op_sel:[1,0,0]
	v_mul_f32_e32 v75, v75, v75
	v_lshl_add_u64 v[76:77], v[76:77], 0, v[176:177]
	v_pk_fma_f32 v[70:71], v[102:103], v[70:71], v[142:143] op_sel:[1,0,0]
	v_pk_fma_f32 v[68:69], v[102:103], v[68:69], v[140:141] op_sel:[1,0,0]
	v_max_f32_e32 v64, 0, v64
	v_max_f32_e32 v65, 0, v65
	v_max_f32_e32 v66, 0, v66
	v_cvt_pk_bf16_f32 v75, v78, v75
	global_store_dwordx4 v[76:77], v[72:75], off
	v_max_f32_e32 v68, 0, v68
	v_max_f32_e32 v67, 0, v67
	v_mul_f32_e32 v72, v64, v64
	v_max_f32_e32 v64, 0, v69
	v_mul_f32_e32 v69, v65, v65
	v_max_f32_e32 v65, 0, v70
	v_mul_f32_e32 v70, v66, v66
	v_max_f32_e32 v66, 0, v71
	v_mul_f32_e32 v68, v68, v68
	v_mul_f32_e32 v64, v64, v64
	v_mul_f32_e32 v65, v65, v65
	v_mul_f32_e32 v66, v66, v66
	v_mul_f32_e32 v67, v67, v67
	v_cvt_pk_bf16_f32 v64, v68, v64
	v_cvt_pk_bf16_f32 v65, v65, v66
	v_cvt_pk_bf16_f32 v66, v72, v69
	v_cvt_pk_bf16_f32 v67, v70, v67
	ds_read2_b64 v[68:71], v175 offset0:128 offset1:144
	global_store_dwordx4 v[76:77], v[64:67], off offset:256
	v_max_f32_e32 v119, 0, v119
	v_mul_f32_e32 v138, v138, v138
	v_add_u32_e32 v64, 0x80, v174
	s_waitcnt lgkmcnt(0)
	v_pk_fma_f32 v[58:59], v[124:125], v[68:69], v[58:59] op_sel_hi:[1,0,1]
	v_pk_fma_f32 v[56:57], v[144:145], v[68:69], v[56:57] op_sel_hi:[1,0,1] neg_lo:[1,0,0] neg_hi:[1,0,0]
	v_pk_fma_f32 v[62:63], v[150:151], v[68:69], v[62:63] op_sel_hi:[1,0,1]
	v_pk_fma_f32 v[60:61], v[148:149], v[68:69], v[60:61] op_sel_hi:[1,0,1] neg_lo:[1,0,0] neg_hi:[1,0,0]
	v_pk_fma_f32 v[58:59], v[68:69], v[58:59], v[154:155] op_sel:[1,0,0]
	v_pk_fma_f32 v[56:57], v[68:69], v[56:57], v[152:153] op_sel:[1,0,0]
	v_pk_fma_f32 v[62:63], v[68:69], v[62:63], v[158:159] op_sel:[1,0,0]
	v_pk_fma_f32 v[60:61], v[68:69], v[60:61], v[156:157] op_sel:[1,0,0]
	v_max_f32_e32 v56, 0, v56
	v_max_f32_e32 v57, 0, v57
	v_max_f32_e32 v58, 0, v58
	v_ashrrev_i32_e32 v65, 31, v64
	v_max_f32_e32 v60, 0, v60
	v_mul_f32_e32 v66, v56, v56
	v_max_f32_e32 v56, 0, v61
	v_mul_f32_e32 v61, v57, v57
	v_max_f32_e32 v57, 0, v62
	v_mul_f32_e32 v62, v58, v58
	v_max_f32_e32 v58, 0, v63
	v_lshl_add_u64 v[64:65], v[64:65], 0, s[20:21]
	v_mul_f32_e32 v60, v60, v60
	v_mul_f32_e32 v56, v56, v56
	v_mul_f32_e32 v57, v57, v57
	v_mul_f32_e32 v58, v58, v58
	v_cvt_pk_bf16_f32 v56, v60, v56
	v_cvt_pk_bf16_f32 v57, v57, v58
	v_cvt_pk_bf16_f32 v58, v66, v61
	v_lshlrev_b64 v[60:61], 13, v[64:65]
	v_pk_fma_f32 v[48:49], v[128:129], v[68:69], v[48:49] op_sel_hi:[1,0,1] neg_lo:[1,0,0] neg_hi:[1,0,0]
	v_max_f32_e32 v59, 0, v59
	v_lshl_add_u64 v[60:61], s[44:45], 0, v[60:61]
	v_pk_fma_f32 v[52:53], v[136:137], v[68:69], v[52:53] op_sel_hi:[1,0,1] neg_lo:[1,0,0] neg_hi:[1,0,0]
	v_pk_fma_f32 v[50:51], v[116:117], v[68:69], v[50:51] op_sel_hi:[1,0,1]
	v_pk_fma_f32 v[48:49], v[68:69], v[48:49], v[132:133] op_sel:[1,0,0]
	v_mul_f32_e32 v59, v59, v59
	v_lshl_add_u64 v[60:61], v[60:61], 0, v[176:177]
	v_pk_fma_f32 v[54:55], v[120:121], v[68:69], v[54:55] op_sel_hi:[1,0,1]
	v_pk_fma_f32 v[52:53], v[68:69], v[52:53], v[140:141] op_sel:[1,0,0]
	v_pk_fma_f32 v[50:51], v[68:69], v[50:51], v[134:135] op_sel:[1,0,0]
	v_max_f32_e32 v48, 0, v48
	v_cvt_pk_bf16_f32 v59, v62, v59
	global_store_dwordx4 v[60:61], v[56:59], off
	v_pk_fma_f32 v[54:55], v[68:69], v[54:55], v[142:143] op_sel:[1,0,0]
	v_max_f32_e32 v49, 0, v49
	v_mul_f32_e32 v56, v48, v48
	v_max_f32_e32 v48, 0, v53
	v_max_f32_e32 v50, 0, v50
	v_max_f32_e32 v52, 0, v52
	v_mul_f32_e32 v48, v48, v48
	v_mul_f32_e32 v53, v49, v49
	v_max_f32_e32 v49, 0, v54
	v_mul_f32_e32 v54, v50, v50
	v_max_f32_e32 v50, 0, v55
	v_max_f32_e32 v51, 0, v51
	v_pk_fma_f32 v[42:43], v[124:125], v[70:71], v[42:43] op_sel_hi:[1,0,1]
	v_pk_fma_f32 v[40:41], v[144:145], v[70:71], v[40:41] op_sel_hi:[1,0,1] neg_lo:[1,0,0] neg_hi:[1,0,0]
	v_mul_f32_e32 v52, v52, v52
	v_mul_f32_e32 v49, v49, v49
	v_mul_f32_e32 v50, v50, v50
	v_mul_f32_e32 v51, v51, v51
	v_cvt_pk_bf16_f32 v48, v52, v48
	v_pk_fma_f32 v[46:47], v[150:151], v[70:71], v[46:47] op_sel_hi:[1,0,1]
	v_pk_fma_f32 v[44:45], v[148:149], v[70:71], v[44:45] op_sel_hi:[1,0,1] neg_lo:[1,0,0] neg_hi:[1,0,0]
	v_pk_fma_f32 v[42:43], v[70:71], v[42:43], v[154:155] op_sel:[1,0,0]
	v_pk_fma_f32 v[40:41], v[70:71], v[40:41], v[152:153] op_sel:[1,0,0]
	v_cvt_pk_bf16_f32 v49, v49, v50
	v_cvt_pk_bf16_f32 v50, v56, v53
	v_cvt_pk_bf16_f32 v51, v54, v51
	global_store_dwordx4 v[60:61], v[48:51], off offset:256
	v_pk_fma_f32 v[46:47], v[70:71], v[46:47], v[158:159] op_sel:[1,0,0]
	v_pk_fma_f32 v[44:45], v[70:71], v[44:45], v[156:157] op_sel:[1,0,0]
	v_add_u32_e32 v48, 0x90, v174
	v_max_f32_e32 v40, 0, v40
	v_max_f32_e32 v41, 0, v41
	v_max_f32_e32 v42, 0, v42
	v_ashrrev_i32_e32 v49, 31, v48
	v_max_f32_e32 v44, 0, v44
	v_mul_f32_e32 v50, v40, v40
	v_max_f32_e32 v40, 0, v45
	v_mul_f32_e32 v45, v41, v41
	v_max_f32_e32 v41, 0, v46
	v_mul_f32_e32 v46, v42, v42
	v_max_f32_e32 v42, 0, v47
	v_lshl_add_u64 v[48:49], v[48:49], 0, s[20:21]
	v_mul_f32_e32 v44, v44, v44
	v_mul_f32_e32 v40, v40, v40
	v_mul_f32_e32 v41, v41, v41
	v_mul_f32_e32 v42, v42, v42
	v_cvt_pk_bf16_f32 v40, v44, v40
	v_cvt_pk_bf16_f32 v41, v41, v42
; #define EPI_FOR_ROWS for (int ai = 0; ai < 2; ++ai) _Pragma("unroll") for (int m = 0; m < 4; ++m)
;     __device__ __forceinline__ void operator()(const f32x4 (&acc)[2][2][4][2], const Unit& u, int wr, int wc, int fr_, int fq_, LAS unsigned char* ldsx) const {
;     ...
;         EPI_FOR_ROWS {
;             const int rl = ai * HALF + wr * 64 + m * 16 + fr; const size_t row = (size_t)u.row0 + rl;
;             float mean = 0.f, rstd = 0.f; if constexpr (CONS) { const f32x2 st = X[rl]; mean = st.x; rstd = st.y; }
;             float s = 0.f, ss = 0.f;
; #pragma unroll
;             for (int bj = 0; bj < 2; ++bj) piece(row, colb + bj * HALF, acc[ai][bj][m][0], acc[ai][bj][m][1], av[bj][0], av[bj][1], bv[bj][0], bv[bj][1], cv[bj][0], cv[bj][1], mean, rstd, s, ss);
	v_cvt_pk_bf16_f32 v42, v50, v45
	v_lshlrev_b64 v[44:45], 13, v[48:49]
	v_pk_fma_f32 v[34:35], v[116:117], v[70:71], v[34:35] op_sel_hi:[1,0,1]
	v_pk_fma_f32 v[32:33], v[128:129], v[70:71], v[32:33] op_sel_hi:[1,0,1] neg_lo:[1,0,0] neg_hi:[1,0,0]
	v_max_f32_e32 v43, 0, v43
	v_lshl_add_u64 v[44:45], s[44:45], 0, v[44:45]
	v_pk_fma_f32 v[38:39], v[120:121], v[70:71], v[38:39] op_sel_hi:[1,0,1]
	v_pk_fma_f32 v[36:37], v[136:137], v[70:71], v[36:37] op_sel_hi:[1,0,1] neg_lo:[1,0,0] neg_hi:[1,0,0]
	v_pk_fma_f32 v[34:35], v[70:71], v[34:35], v[134:135] op_sel:[1,0,0]
	v_pk_fma_f32 v[32:33], v[70:71], v[32:33], v[132:133] op_sel:[1,0,0]
	v_mul_f32_e32 v43, v43, v43
	v_lshl_add_u64 v[44:45], v[44:45], 0, v[176:177]
	v_pk_fma_f32 v[38:39], v[70:71], v[38:39], v[142:143] op_sel:[1,0,0]
	v_pk_fma_f32 v[36:37], v[70:71], v[36:37], v[140:141] op_sel:[1,0,0]
	v_max_f32_e32 v32, 0, v32
	v_max_f32_e32 v33, 0, v33
	v_max_f32_e32 v34, 0, v34
	v_cvt_pk_bf16_f32 v43, v46, v43
	global_store_dwordx4 v[44:45], v[40:43], off
	v_max_f32_e32 v36, 0, v36
	v_max_f32_e32 v35, 0, v35
	v_mul_f32_e32 v40, v32, v32
	v_max_f32_e32 v32, 0, v37
	v_mul_f32_e32 v37, v33, v33
	v_max_f32_e32 v33, 0, v38
	v_mul_f32_e32 v38, v34, v34
	v_max_f32_e32 v34, 0, v39
	v_mul_f32_e32 v36, v36, v36
	v_mul_f32_e32 v32, v32, v32
	v_mul_f32_e32 v33, v33, v33
	v_mul_f32_e32 v34, v34, v34
	v_mul_f32_e32 v35, v35, v35
	v_cvt_pk_bf16_f32 v32, v36, v32
	v_cvt_pk_bf16_f32 v33, v33, v34
	v_cvt_pk_bf16_f32 v34, v40, v37
	v_cvt_pk_bf16_f32 v35, v38, v35
	ds_read2_b64 v[36:39], v175 offset0:160 offset1:176
	global_store_dwordx4 v[44:45], v[32:35], off offset:256
	v_mul_f32_e32 v139, v139, v139
	v_mul_f32_e32 v118, v118, v118
	v_add_u32_e32 v32, 0xa0, v174
	s_waitcnt lgkmcnt(0)
; #define PG8_BAR __builtin_amdgcn_s_barrier()
; #define EPI_FOR_ROWS for (int ai = 0; ai < 2; ++ai) _Pragma("unroll") for (int m = 0; m < 4; ++m)
; template <class Epi, class Sched, bool ALIGN_EPI>
; __device__ __forceinline__ void gemm_phase(LAS unsigned char* lds, const GemmDesc g, const Sched& S, const Epi& E) {
;     ...
;         if (!has_next) break;
; #pragma unroll
;         for (int a = 0; a < 2; ++a)
; #pragma unroll
;             for (int b = 0; b < 2; ++b)
; #pragma unroll
;                 for (int m = 0; m < 4; ++m)
; #pragma unroll
;                     for (int n = 0; n < 2; ++n) acc[a][b][m][n] = (f32x4){0.f, 0.f, 0.f, 0.f};
;         cur = nxt; cA = nA; cB = nB; ++ui;
;         if constexpr (ALIGN_EPI) { if (wr == 1) PG8_BAR; }
;     }
;     __device__ __forceinline__ void operator()(const f32x4 (&acc)[2][2][4][2], const Unit& u, int wr, int wc, int fr_, int fq_, LAS unsigned char* ldsx) const {
;     ...
;         EPI_FOR_ROWS {
;             const int rl = ai * HALF + wr * 64 + m * 16 + fr; const size_t row = (size_t)u.row0 + rl;
;             float mean = 0.f, rstd = 0.f; if constexpr (CONS) { const f32x2 st = X[rl]; mean = st.x; rstd = st.y; }
;             float s = 0.f, ss = 0.f;
; #pragma unroll
;             for (int bj = 0; bj < 2; ++bj) piece(row, colb + bj * HALF, acc[ai][bj][m][0], acc[ai][bj][m][1], av[bj][0], av[bj][1], bv[bj][0], bv[bj][1], cv[bj][0], cv[bj][1], mean, rstd, s, ss);
	v_pk_fma_f32 v[26:27], v[124:125], v[36:37], v[26:27] op_sel_hi:[1,0,1]
	v_pk_fma_f32 v[24:25], v[144:145], v[36:37], v[24:25] op_sel_hi:[1,0,1] neg_lo:[1,0,0] neg_hi:[1,0,0]
	v_pk_fma_f32 v[30:31], v[150:151], v[36:37], v[30:31] op_sel_hi:[1,0,1]
	v_pk_fma_f32 v[28:29], v[148:149], v[36:37], v[28:29] op_sel_hi:[1,0,1] neg_lo:[1,0,0] neg_hi:[1,0,0]
	v_pk_fma_f32 v[26:27], v[36:37], v[26:27], v[154:155] op_sel:[1,0,0]
	v_pk_fma_f32 v[24:25], v[36:37], v[24:25], v[152:153] op_sel:[1,0,0]
	v_pk_fma_f32 v[30:31], v[36:37], v[30:31], v[158:159] op_sel:[1,0,0]
	v_pk_fma_f32 v[28:29], v[36:37], v[28:29], v[156:157] op_sel:[1,0,0]
	v_max_f32_e32 v24, 0, v24
	v_max_f32_e32 v25, 0, v25
	v_max_f32_e32 v26, 0, v26
	v_ashrrev_i32_e32 v33, 31, v32
	v_max_f32_e32 v28, 0, v28
	v_mul_f32_e32 v34, v24, v24
	v_max_f32_e32 v24, 0, v29
	v_mul_f32_e32 v29, v25, v25
	v_max_f32_e32 v25, 0, v30
	v_mul_f32_e32 v30, v26, v26
	v_max_f32_e32 v26, 0, v31
	v_lshl_add_u64 v[32:33], v[32:33], 0, s[20:21]
	v_mul_f32_e32 v28, v28, v28
	v_mul_f32_e32 v24, v24, v24
	v_mul_f32_e32 v25, v25, v25
	v_mul_f32_e32 v26, v26, v26
	v_cvt_pk_bf16_f32 v24, v28, v24
	v_cvt_pk_bf16_f32 v25, v25, v26
	v_cvt_pk_bf16_f32 v26, v34, v29
	v_lshlrev_b64 v[28:29], 13, v[32:33]
	v_pk_fma_f32 v[16:17], v[128:129], v[36:37], v[16:17] op_sel_hi:[1,0,1] neg_lo:[1,0,0] neg_hi:[1,0,0]
	v_max_f32_e32 v27, 0, v27
	v_lshl_add_u64 v[28:29], s[44:45], 0, v[28:29]
	v_pk_fma_f32 v[20:21], v[136:137], v[36:37], v[20:21] op_sel_hi:[1,0,1] neg_lo:[1,0,0] neg_hi:[1,0,0]
	v_pk_fma_f32 v[18:19], v[116:117], v[36:37], v[18:19] op_sel_hi:[1,0,1]
	v_pk_fma_f32 v[16:17], v[36:37], v[16:17], v[132:133] op_sel:[1,0,0]
	v_mul_f32_e32 v27, v27, v27
	v_lshl_add_u64 v[28:29], v[28:29], 0, v[176:177]
	v_pk_fma_f32 v[22:23], v[120:121], v[36:37], v[22:23] op_sel_hi:[1,0,1]
	v_pk_fma_f32 v[20:21], v[36:37], v[20:21], v[140:141] op_sel:[1,0,0]
	v_pk_fma_f32 v[18:19], v[36:37], v[18:19], v[134:135] op_sel:[1,0,0]
	v_max_f32_e32 v16, 0, v16
	v_cvt_pk_bf16_f32 v27, v30, v27
	global_store_dwordx4 v[28:29], v[24:27], off
	v_pk_fma_f32 v[22:23], v[36:37], v[22:23], v[142:143] op_sel:[1,0,0]
	v_max_f32_e32 v17, 0, v17
	v_mul_f32_e32 v24, v16, v16
	v_max_f32_e32 v16, 0, v21
	v_max_f32_e32 v18, 0, v18
	v_max_f32_e32 v20, 0, v20
	v_mul_f32_e32 v16, v16, v16
	v_mul_f32_e32 v21, v17, v17
	v_max_f32_e32 v17, 0, v22
	v_mul_f32_e32 v22, v18, v18
	v_max_f32_e32 v18, 0, v23
	v_max_f32_e32 v19, 0, v19
	v_pk_fma_f32 v[10:11], v[124:125], v[38:39], v[10:11] op_sel_hi:[1,0,1]
	v_pk_fma_f32 v[8:9], v[144:145], v[38:39], v[8:9] op_sel_hi:[1,0,1] neg_lo:[1,0,0] neg_hi:[1,0,0]
	v_mul_f32_e32 v20, v20, v20
	v_mul_f32_e32 v17, v17, v17
	v_mul_f32_e32 v18, v18, v18
	v_mul_f32_e32 v19, v19, v19
	v_cvt_pk_bf16_f32 v16, v20, v16
	v_pk_fma_f32 v[14:15], v[150:151], v[38:39], v[14:15] op_sel_hi:[1,0,1]
	v_pk_fma_f32 v[12:13], v[148:149], v[38:39], v[12:13] op_sel_hi:[1,0,1] neg_lo:[1,0,0] neg_hi:[1,0,0]
	v_pk_fma_f32 v[10:11], v[38:39], v[10:11], v[154:155] op_sel:[1,0,0]
	v_pk_fma_f32 v[8:9], v[38:39], v[8:9], v[152:153] op_sel:[1,0,0]
	v_cvt_pk_bf16_f32 v17, v17, v18
	v_cvt_pk_bf16_f32 v18, v24, v21
	v_cvt_pk_bf16_f32 v19, v22, v19
	global_store_dwordx4 v[28:29], v[16:19], off offset:256
	v_pk_fma_f32 v[14:15], v[38:39], v[14:15], v[158:159] op_sel:[1,0,0]
	v_pk_fma_f32 v[12:13], v[38:39], v[12:13], v[156:157] op_sel:[1,0,0]
	v_add_u32_e32 v16, 0xb0, v174
	v_max_f32_e32 v8, 0, v8
	v_max_f32_e32 v9, 0, v9
	v_max_f32_e32 v10, 0, v10
	v_ashrrev_i32_e32 v17, 31, v16
	v_max_f32_e32 v12, 0, v12
	v_mul_f32_e32 v18, v8, v8
	v_max_f32_e32 v8, 0, v13
	v_mul_f32_e32 v13, v9, v9
	v_max_f32_e32 v9, 0, v14
	v_mul_f32_e32 v14, v10, v10
	v_max_f32_e32 v10, 0, v15
	v_lshl_add_u64 v[16:17], v[16:17], 0, s[20:21]
	v_mul_f32_e32 v12, v12, v12
	v_mul_f32_e32 v8, v8, v8
	v_mul_f32_e32 v9, v9, v9
	v_mul_f32_e32 v10, v10, v10
	v_cvt_pk_bf16_f32 v8, v12, v8
	v_cvt_pk_bf16_f32 v9, v9, v10
	v_cvt_pk_bf16_f32 v10, v18, v13
	v_lshlrev_b64 v[12:13], 13, v[16:17]
	v_pk_fma_f32 v[2:3], v[116:117], v[38:39], v[2:3] op_sel_hi:[1,0,1]
	v_pk_fma_f32 v[0:1], v[128:129], v[38:39], v[0:1] op_sel_hi:[1,0,1] neg_lo:[1,0,0] neg_hi:[1,0,0]
	v_max_f32_e32 v11, 0, v11
	v_lshl_add_u64 v[12:13], s[44:45], 0, v[12:13]
	v_pk_fma_f32 v[6:7], v[120:121], v[38:39], v[6:7] op_sel_hi:[1,0,1]
	v_pk_fma_f32 v[4:5], v[136:137], v[38:39], v[4:5] op_sel_hi:[1,0,1] neg_lo:[1,0,0] neg_hi:[1,0,0]
	v_pk_fma_f32 v[2:3], v[38:39], v[2:3], v[134:135] op_sel:[1,0,0]
	v_pk_fma_f32 v[0:1], v[38:39], v[0:1], v[132:133] op_sel:[1,0,0]
	v_mul_f32_e32 v11, v11, v11
	v_lshl_add_u64 v[12:13], v[12:13], 0, v[176:177]
	v_pk_fma_f32 v[6:7], v[38:39], v[6:7], v[142:143] op_sel:[1,0,0]
	v_pk_fma_f32 v[4:5], v[38:39], v[4:5], v[140:141] op_sel:[1,0,0]
	v_max_f32_e32 v0, 0, v0
	v_max_f32_e32 v1, 0, v1
	v_max_f32_e32 v2, 0, v2
	v_cvt_pk_bf16_f32 v11, v14, v11
	global_store_dwordx4 v[12:13], v[8:11], off
	v_max_f32_e32 v3, 0, v3
	v_max_f32_e32 v4, 0, v4
	v_mul_f32_e32 v8, v0, v0
	v_max_f32_e32 v0, 0, v5
	v_mul_f32_e32 v5, v1, v1
	v_max_f32_e32 v1, 0, v6
	v_mul_f32_e32 v6, v2, v2
	v_max_f32_e32 v2, 0, v7
	v_mul_f32_e32 v0, v0, v0
	v_mul_f32_e32 v1, v1, v1
	v_mul_f32_e32 v2, v2, v2
	v_mul_f32_e32 v3, v3, v3
	s_mov_b64 s[20:21], -1
	v_mul_f32_e32 v119, v119, v119
	v_cvt_pk_bf16_f32 v188, v138, v139
	v_cvt_pk_bf16_f32 v189, v130, v119
	v_cvt_pk_bf16_f32 v190, v184, v185
	v_cvt_pk_bf16_f32 v191, v118, v131
	global_store_dwordx4 v[192:193], v[188:191], off offset:256
	v_mul_f32_e32 v4, v4, v4
	v_cvt_pk_bf16_f32 v0, v4, v0
	v_cvt_pk_bf16_f32 v1, v1, v2
	v_cvt_pk_bf16_f32 v2, v8, v5
	v_cvt_pk_bf16_f32 v3, v6, v3
	global_store_dwordx4 v[12:13], v[0:3], off offset:256
	s_cbranch_vccnz .LBB0_1369
	s_andn2_b64 vcc, exec, s[12:13]
	s_cbranch_vccnz .LBB0_1368
	s_barrier
	s_branch .LBB0_1368
